# one static s_setprio 1 for waves 0-3 across the prompt-attention tile loop (reset after the loop)
# speedup vs baseline: 1.0161x; 1.0161x over previous
;     ...
;         gload(0); lstore(0); if (ntiles > 1) gload(1);
;         __syncthreads();
;         for (int t = 0; t < ntiles; ++t) { const int cur = t & 1;
;             if (t + 1 < ntiles) lstore(cur ^ 1);
;             if (t + 2 < ntiles) gload(t + 2);
.LBB0_1906:
	s_lshl_b32 s0, s15, 2
	v_ashrrev_i32_e32 v185, 31, v184
	v_mul_u32_u24_e32 v14, 0x88, v208
	s_add_i32 s13, s13, 5
	s_add_i32 s46, s16, 0x80
	s_sub_i32 s15, 0, s0
	s_movk_i32 s16, 0xff80
	s_waitcnt lgkmcnt(0)
	s_barrier
	s_sub_i32 s0, s13, s12
	s_cmp_le_i32 s0, 2
	s_cbranch_scc1 .Lprio_skip
	s_setprio 1
